# GEMM K-loop first load segment: the 16 ds_read_b128 issue ahead of the 11 scalar pointer/select instructions (pure reorder); on top of m15
# baseline (speedup 1.0000x reference)
; #define PG8_STAGE(bufoff, gbase, voff) do { _Pragma("unroll") for (int _i = 0; _i < 2; ++_i) \
;         __builtin_amdgcn_global_load_lds((const unsigned*)((const char*)(gbase) + (voff)[_i]), (LAS unsigned*)(lds + (bufoff) + ldsw + _i * 8192), 16, 0, 0); } while (0)
; #define PG8_LDA(dst, b, h) do { _Pragma("unroll") for (int m = 0; m < 4; ++m) _Pragma("unroll") for (int k = 0; k < 2; ++k) dst[m][k] = *(const LAS bf16x8*)(lds + PG8_SA(b, h) + aoff + m * 2048 + k * 1024); } while (0)
; #define PG8_LDB(dst, b, h) do { _Pragma("unroll") for (int n = 0; n < 2; ++n) _Pragma("unroll") for (int k = 0; k < 2; ++k) dst[n][k] = *(const LAS bf16x8*)(lds + PG8_SB(b, h) + boff + n * 2048 + k * 1024); } while (0)
; #define PG8_MMA(ai, bj, At, Bt) do { __builtin_amdgcn_s_setprio(1); _Pragma("unroll") for (int m = 0; m < 4; ++m) _Pragma("unroll") for (int n = 0; n < 2; ++n) _Pragma("unroll") for (int k = 0; k < 2; ++k) \
;         acc[ai][bj][m][n] = __builtin_amdgcn_mfma_f32_16x16x32_bf16(Bt[n][k], At[m][k], acc[ai][bj][m][n], 0, 0, 0); __builtin_amdgcn_s_setprio(0); } while (0)
; #define PG8_WAIT_V(n) asm volatile("s_waitcnt vmcnt(" #n ")" ::: "memory")
; #define PG8_WAIT_L(n) asm volatile("s_waitcnt lgkmcnt(" #n ")" ::: "memory")
; #define PG8_BAR __builtin_amdgcn_s_barrier()
; #define PG8_SCHED __builtin_amdgcn_sched_barrier(0)
; __device__ __forceinline__ void gemm_phase(LAS unsigned char* lds, const GP p, const int tid) {
;     ...
;             const char* a1 = cA + (size_t)(t + 1) * kstep;
;             const char* a2 = last ? nA : cA + (size_t)(t + 2) * kstep; const char* b2 = last ? nB : cB + (size_t)(t + 2) * kstep;
;             const char* a3 = a2 + kstep; const char* b3 = b2 + kstep;
;             PG8_LDB(B0, 0, 0); PG8_LDB(B1, 0, 1); PG8_SCHED; PG8_LDA(At, 0, 0); PG8_STAGE(PG8_SA(1, 1), a1 + hstep, voffA);
;             PG8_WAIT_V(8); PG8_WAIT_L(0); PG8_BAR; PG8_MMA(0, 0, At, B0); PG8_MMA(0, 1, At, B1); PG8_BAR; PG8_SCHED;
;             PG8_LDA(At, 0, 1); PG8_STAGE(PG8_SB(0, 0), b2, voffB); PG8_STAGE(PG8_SB(0, 1), b2 + hstep, voffB); PG8_STAGE(PG8_SA(0, 0), a2, voffA);
;             PG8_WAIT_V(8); PG8_WAIT_L(0); PG8_BAR; PG8_MMA(1, 0, At, B0); PG8_MMA(1, 1, At, B1); PG8_BAR; PG8_SCHED;
.Lpeel_body:
	ds_read_b128 v[130:133], v238
	ds_read_b128 v[134:137], v238 offset:1024
	ds_read_b128 v[138:141], v238 offset:2048
	ds_read_b128 v[180:183], v238 offset:3072
	ds_read_b128 v[184:187], v239
	ds_read_b128 v[188:191], v239 offset:1024
	ds_read_b128 v[192:195], v239 offset:2048
	ds_read_b128 v[196:199], v239 offset:3072
	ds_read_b128 v[200:203], v167
	ds_read_b128 v[204:207], v167 offset:1024
	ds_read_b128 v[208:211], v167 offset:2048
	ds_read_b128 v[218:221], v167 offset:3072
	ds_read_b128 v[222:225], v167 offset:4096
	ds_read_b128 v[226:229], v167 offset:5120
	ds_read_b128 v[230:233], v167 offset:6144
	ds_read_b128 v[234:237], v167 offset:7168
	s_add_i32 s98, s98, 2
	s_add_u32 s43, s82, 0x80
	s_addc_u32 s99, s83, 0
	s_and_b64 s[86:87], s[84:85], exec
	s_cselect_b32 s87, s77, s99
	s_cselect_b32 s86, s76, s43
	s_add_i32 s43, 0, 0x10000
	s_and_b64 s[84:85], s[84:85], exec
	s_cselect_b32 s85, s79, s91
	s_cselect_b32 s84, s78, s81
	s_add_i32 m0, s53, 0xc000
	s_add_i32 s99, 0, 0x14000
	global_load_lds_dwordx4 v160, s[82:83]
	s_add_i32 m0, s53, 0xe000
	s_nop 0
	global_load_lds_dwordx4 v162, s[82:83]
	s_waitcnt vmcnt(8)
	s_waitcnt lgkmcnt(0)
	s_barrier
	s_setprio 1
	v_mfma_f32_16x16x32_bf16 v[124:127], v[130:133], v[200:203], 0
	v_mfma_f32_16x16x32_bf16 v[120:123], v[138:141], v[200:203], 0
	v_mfma_f32_16x16x32_bf16 v[108:111], v[130:133], v[208:211], 0
	v_mfma_f32_16x16x32_bf16 v[104:107], v[138:141], v[208:211], 0
	v_mfma_f32_16x16x32_bf16 v[92:95], v[130:133], v[222:225], 0
	v_mfma_f32_16x16x32_bf16 v[88:91], v[138:141], v[222:225], 0
	v_mfma_f32_16x16x32_bf16 v[76:79], v[130:133], v[230:233], 0
	v_mfma_f32_16x16x32_bf16 v[72:75], v[138:141], v[230:233], 0
	v_mfma_f32_16x16x32_bf16 v[124:127], v[134:137], v[204:207], v[124:127]
	v_mfma_f32_16x16x32_bf16 v[120:123], v[180:183], v[204:207], v[120:123]
	v_mfma_f32_16x16x32_bf16 v[108:111], v[134:137], v[218:221], v[108:111]
	v_mfma_f32_16x16x32_bf16 v[104:107], v[180:183], v[218:221], v[104:107]
	v_mfma_f32_16x16x32_bf16 v[92:95], v[134:137], v[226:229], v[92:95]
	v_mfma_f32_16x16x32_bf16 v[88:91], v[180:183], v[226:229], v[88:91]
	v_mfma_f32_16x16x32_bf16 v[76:79], v[134:137], v[234:237], v[76:79]
	v_mfma_f32_16x16x32_bf16 v[72:75], v[180:183], v[234:237], v[72:75]
	s_setprio 0
	s_setprio 1
	v_mfma_f32_16x16x32_bf16 v[116:119], v[184:187], v[200:203], 0
	v_mfma_f32_16x16x32_bf16 v[112:115], v[192:195], v[200:203], 0
	v_mfma_f32_16x16x32_bf16 v[100:103], v[184:187], v[208:211], 0
	v_mfma_f32_16x16x32_bf16 v[96:99], v[192:195], v[208:211], 0
	v_mfma_f32_16x16x32_bf16 v[84:87], v[184:187], v[222:225], 0
	v_mfma_f32_16x16x32_bf16 v[80:83], v[192:195], v[222:225], 0
	v_mfma_f32_16x16x32_bf16 v[68:71], v[184:187], v[230:233], 0
	v_mfma_f32_16x16x32_bf16 v[64:67], v[192:195], v[230:233], 0
	v_mfma_f32_16x16x32_bf16 v[116:119], v[188:191], v[204:207], v[116:119]
	v_mfma_f32_16x16x32_bf16 v[112:115], v[196:199], v[204:207], v[112:115]
	v_mfma_f32_16x16x32_bf16 v[100:103], v[188:191], v[218:221], v[100:103]
	v_mfma_f32_16x16x32_bf16 v[96:99], v[196:199], v[218:221], v[96:99]
	v_mfma_f32_16x16x32_bf16 v[84:87], v[188:191], v[226:229], v[84:87]
	v_mfma_f32_16x16x32_bf16 v[80:83], v[196:199], v[226:229], v[80:83]
	v_mfma_f32_16x16x32_bf16 v[68:71], v[188:191], v[234:237], v[68:71]
	v_mfma_f32_16x16x32_bf16 v[64:67], v[196:199], v[234:237], v[64:67]
	s_setprio 0
	s_barrier
	s_add_i32 s43, s43, s52
	s_mov_b64 s[100:101], s[84:85]
	s_mov_b32 m0, s43
	ds_read_b128 v[200:203], v167 offset:16384
	ds_read_b128 v[204:207], v167 offset:17408
	ds_read_b128 v[208:211], v167 offset:18432
	ds_read_b128 v[218:221], v167 offset:19456
	ds_read_b128 v[222:225], v167 offset:20480
	ds_read_b128 v[226:229], v167 offset:21504
	ds_read_b128 v[230:233], v167 offset:22528
	ds_read_b128 v[234:237], v167 offset:23552
	global_load_lds_dwordx4 v148, s[84:85]
	s_add_i32 m0, s43, 0x2000
	s_add_i32 s43, s99, s52
	global_load_lds_dwordx4 v152, s[84:85]
	s_add_u32 s84, s84, s74
	s_addc_u32 s85, s85, 0
	s_mov_b32 m0, s43
	s_nop 0
	global_load_lds_dwordx4 v148, s[84:85]
	s_add_i32 m0, s43, 0x2000
	s_nop 0
	global_load_lds_dwordx4 v152, s[84:85]
	s_mov_b32 m0, s53
	s_nop 0
	global_load_lds_dwordx4 v146, s[86:87]
	s_mov_b32 m0, s54
	s_nop 0
	global_load_lds_dwordx4 v150, s[86:87]
	s_waitcnt vmcnt(8)
	s_waitcnt lgkmcnt(0)
	s_barrier
	s_setprio 1
	v_mfma_f32_16x16x32_bf16 v[60:63], v[130:133], v[200:203], 0
	v_mfma_f32_16x16x32_bf16 v[56:59], v[138:141], v[200:203], 0
	v_mfma_f32_16x16x32_bf16 v[44:47], v[130:133], v[208:211], 0
	v_mfma_f32_16x16x32_bf16 v[40:43], v[138:141], v[208:211], 0
	v_mfma_f32_16x16x32_bf16 v[28:31], v[130:133], v[222:225], 0
	v_mfma_f32_16x16x32_bf16 v[24:27], v[138:141], v[222:225], 0
	v_mfma_f32_16x16x32_bf16 v[12:15], v[130:133], v[230:233], 0
	v_mfma_f32_16x16x32_bf16 v[8:11], v[138:141], v[230:233], 0
	v_mfma_f32_16x16x32_bf16 v[60:63], v[134:137], v[204:207], v[60:63]
	v_mfma_f32_16x16x32_bf16 v[56:59], v[180:183], v[204:207], v[56:59]
	v_mfma_f32_16x16x32_bf16 v[44:47], v[134:137], v[218:221], v[44:47]
	v_mfma_f32_16x16x32_bf16 v[40:43], v[180:183], v[218:221], v[40:43]
	v_mfma_f32_16x16x32_bf16 v[28:31], v[134:137], v[226:229], v[28:31]
	v_mfma_f32_16x16x32_bf16 v[24:27], v[180:183], v[226:229], v[24:27]
	v_mfma_f32_16x16x32_bf16 v[12:15], v[134:137], v[234:237], v[12:15]
	v_mfma_f32_16x16x32_bf16 v[8:11], v[180:183], v[234:237], v[8:11]
	s_setprio 0
	s_setprio 1
	v_mfma_f32_16x16x32_bf16 v[52:55], v[184:187], v[200:203], 0
	v_mfma_f32_16x16x32_bf16 v[48:51], v[192:195], v[200:203], 0
	v_mfma_f32_16x16x32_bf16 v[36:39], v[184:187], v[208:211], 0
	v_mfma_f32_16x16x32_bf16 v[32:35], v[192:195], v[208:211], 0
	v_mfma_f32_16x16x32_bf16 v[20:23], v[184:187], v[222:225], 0
	v_mfma_f32_16x16x32_bf16 v[16:19], v[192:195], v[222:225], 0
	v_mfma_f32_16x16x32_bf16 v[4:7], v[184:187], v[230:233], 0
	v_mfma_f32_16x16x32_bf16 v[0:3], v[192:195], v[230:233], 0
	v_mfma_f32_16x16x32_bf16 v[52:55], v[188:191], v[204:207], v[52:55]
	v_mfma_f32_16x16x32_bf16 v[48:51], v[196:199], v[204:207], v[48:51]
	v_mfma_f32_16x16x32_bf16 v[36:39], v[188:191], v[218:221], v[36:39]
	v_mfma_f32_16x16x32_bf16 v[32:35], v[196:199], v[218:221], v[32:35]
	v_mfma_f32_16x16x32_bf16 v[20:23], v[188:191], v[226:229], v[20:23]
	v_mfma_f32_16x16x32_bf16 v[16:19], v[196:199], v[226:229], v[16:19]
	v_mfma_f32_16x16x32_bf16 v[4:7], v[188:191], v[234:237], v[4:7]
	v_mfma_f32_16x16x32_bf16 v[0:3], v[196:199], v[234:237], v[0:3]
	s_setprio 0
	s_barrier
; #define PG8_STAGE(bufoff, gbase, voff) do { _Pragma("unroll") for (int _i = 0; _i < 2; ++_i) \
;         __builtin_amdgcn_global_load_lds((const unsigned*)((const char*)(gbase) + (voff)[_i]), (LAS unsigned*)(lds + (bufoff) + ldsw + _i * 8192), 16, 0, 0); } while (0)
; #define PG8_LDA(dst, b, h) do { _Pragma("unroll") for (int m = 0; m < 4; ++m) _Pragma("unroll") for (int k = 0; k < 2; ++k) dst[m][k] = *(const LAS bf16x8*)(lds + PG8_SA(b, h) + aoff + m * 2048 + k * 1024); } while (0)
; #define PG8_LDB(dst, b, h) do { _Pragma("unroll") for (int n = 0; n < 2; ++n) _Pragma("unroll") for (int k = 0; k < 2; ++k) dst[n][k] = *(const LAS bf16x8*)(lds + PG8_SB(b, h) + boff + n * 2048 + k * 1024); } while (0)
; #define PG8_MMA(ai, bj, At, Bt) do { __builtin_amdgcn_s_setprio(1); _Pragma("unroll") for (int m = 0; m < 4; ++m) _Pragma("unroll") for (int n = 0; n < 2; ++n) _Pragma("unroll") for (int k = 0; k < 2; ++k) \
;         acc[ai][bj][m][n] = __builtin_amdgcn_mfma_f32_16x16x32_bf16(Bt[n][k], At[m][k], acc[ai][bj][m][n], 0, 0, 0); __builtin_amdgcn_s_setprio(0); } while (0)
; #define PG8_WAIT_V(n) asm volatile("s_waitcnt vmcnt(" #n ")" ::: "memory")
; #define PG8_WAIT_L(n) asm volatile("s_waitcnt lgkmcnt(" #n ")" ::: "memory")
; #define PG8_BAR __builtin_amdgcn_s_barrier()
; #define PG8_SCHED __builtin_amdgcn_sched_barrier(0)
; __device__ __forceinline__ void gemm_phase(LAS unsigned char* lds, const GP p, const int tid) {
;     ...
;             PG8_LDB(B0, 1, 0); PG8_LDB(B1, 1, 1); PG8_SCHED; PG8_LDA(At, 1, 0); PG8_STAGE(PG8_SA(0, 1), a2 + hstep, voffA);
;             PG8_WAIT_V(8); PG8_WAIT_L(0); PG8_BAR; PG8_MMA(0, 0, At, B0); PG8_MMA(0, 1, At, B1); PG8_BAR; PG8_SCHED;
;             PG8_LDA(At, 1, 1); PG8_STAGE(PG8_SB(1, 0), b3, voffB); PG8_STAGE(PG8_SB(1, 1), b3 + hstep, voffB); PG8_STAGE(PG8_SA(1, 0), a3, voffA);
;             PG8_WAIT_V(8); PG8_WAIT_L(0); PG8_BAR; PG8_MMA(1, 0, At, B0); PG8_MMA(1, 1, At, B1); PG8_BAR; PG8_SCHED;
;         }
	s_add_i32 s43, 0, 0x18000
	s_add_i32 s99, 0, 0x1c000
	ds_read_b128 v[130:133], v240
	ds_read_b128 v[134:137], v240 offset:1024
	ds_read_b128 v[138:141], v240 offset:2048
	ds_read_b128 v[180:183], v240 offset:3072
	ds_read_b128 v[184:187], v241
	ds_read_b128 v[188:191], v241 offset:1024
	ds_read_b128 v[192:195], v241 offset:2048
	ds_read_b128 v[196:199], v241 offset:3072
	s_add_u32 s84, s86, s74
	s_addc_u32 s85, s87, 0
	s_mov_b32 m0, s55
	ds_read_b128 v[200:203], v167 offset:32768
	ds_read_b128 v[204:207], v167 offset:33792
	ds_read_b128 v[208:211], v167 offset:34816
	ds_read_b128 v[218:221], v167 offset:35840
	ds_read_b128 v[222:225], v167 offset:36864
	ds_read_b128 v[226:229], v167 offset:37888
	ds_read_b128 v[230:233], v167 offset:38912
	ds_read_b128 v[234:237], v167 offset:39936
	global_load_lds_dwordx4 v146, s[84:85]
	s_mov_b32 m0, s56
	s_nop 0
	global_load_lds_dwordx4 v150, s[84:85]
	s_waitcnt vmcnt(8)
	s_waitcnt lgkmcnt(0)
	s_barrier
	s_setprio 1
	v_mfma_f32_16x16x32_bf16 v[124:127], v[130:133], v[200:203], v[124:127]
	v_mfma_f32_16x16x32_bf16 v[120:123], v[138:141], v[200:203], v[120:123]
	v_mfma_f32_16x16x32_bf16 v[108:111], v[130:133], v[208:211], v[108:111]
	v_mfma_f32_16x16x32_bf16 v[104:107], v[138:141], v[208:211], v[104:107]
	v_mfma_f32_16x16x32_bf16 v[92:95], v[130:133], v[222:225], v[92:95]
	v_mfma_f32_16x16x32_bf16 v[88:91], v[138:141], v[222:225], v[88:91]
	v_mfma_f32_16x16x32_bf16 v[76:79], v[130:133], v[230:233], v[76:79]
	v_mfma_f32_16x16x32_bf16 v[72:75], v[138:141], v[230:233], v[72:75]
	v_mfma_f32_16x16x32_bf16 v[124:127], v[134:137], v[204:207], v[124:127]
	v_mfma_f32_16x16x32_bf16 v[120:123], v[180:183], v[204:207], v[120:123]
	v_mfma_f32_16x16x32_bf16 v[108:111], v[134:137], v[218:221], v[108:111]
	v_mfma_f32_16x16x32_bf16 v[104:107], v[180:183], v[218:221], v[104:107]
	v_mfma_f32_16x16x32_bf16 v[92:95], v[134:137], v[226:229], v[92:95]
	v_mfma_f32_16x16x32_bf16 v[88:91], v[180:183], v[226:229], v[88:91]
	v_mfma_f32_16x16x32_bf16 v[76:79], v[134:137], v[234:237], v[76:79]
	v_mfma_f32_16x16x32_bf16 v[72:75], v[180:183], v[234:237], v[72:75]
	s_setprio 0
	s_setprio 1
	v_mfma_f32_16x16x32_bf16 v[116:119], v[184:187], v[200:203], v[116:119]
	v_mfma_f32_16x16x32_bf16 v[112:115], v[192:195], v[200:203], v[112:115]
	v_mfma_f32_16x16x32_bf16 v[100:103], v[184:187], v[208:211], v[100:103]
	v_mfma_f32_16x16x32_bf16 v[96:99], v[192:195], v[208:211], v[96:99]
	v_mfma_f32_16x16x32_bf16 v[84:87], v[184:187], v[222:225], v[84:87]
	v_mfma_f32_16x16x32_bf16 v[80:83], v[192:195], v[222:225], v[80:83]
	v_mfma_f32_16x16x32_bf16 v[68:71], v[184:187], v[230:233], v[68:71]
	v_mfma_f32_16x16x32_bf16 v[64:67], v[192:195], v[230:233], v[64:67]
	v_mfma_f32_16x16x32_bf16 v[116:119], v[188:191], v[204:207], v[116:119]
	v_mfma_f32_16x16x32_bf16 v[112:115], v[196:199], v[204:207], v[112:115]
	v_mfma_f32_16x16x32_bf16 v[100:103], v[188:191], v[218:221], v[100:103]
	v_mfma_f32_16x16x32_bf16 v[96:99], v[196:199], v[218:221], v[96:99]
	v_mfma_f32_16x16x32_bf16 v[84:87], v[188:191], v[226:229], v[84:87]
	v_mfma_f32_16x16x32_bf16 v[80:83], v[196:199], v[226:229], v[80:83]
	v_mfma_f32_16x16x32_bf16 v[68:71], v[188:191], v[234:237], v[68:71]
	v_mfma_f32_16x16x32_bf16 v[64:67], v[196:199], v[234:237], v[64:67]
	s_setprio 0
	s_barrier
	s_add_i32 s43, s43, s52
	s_add_u32 s100, s100, 0x80
	s_addc_u32 s101, s101, 0
	s_mov_b32 m0, s43
	ds_read_b128 v[200:203], v167 offset:49152
	ds_read_b128 v[204:207], v167 offset:50176
	ds_read_b128 v[208:211], v167 offset:51200
	ds_read_b128 v[218:221], v167 offset:52224
	ds_read_b128 v[222:225], v167 offset:53248
	ds_read_b128 v[226:229], v167 offset:54272
	ds_read_b128 v[230:233], v167 offset:55296
	ds_read_b128 v[234:237], v167 offset:56320
	global_load_lds_dwordx4 v148, s[100:101]
	s_add_i32 m0, s43, 0x2000
	s_add_i32 s43, s99, s52
	global_load_lds_dwordx4 v152, s[100:101]
	s_add_u32 s100, s100, s74
	s_addc_u32 s101, s101, 0
	s_mov_b32 m0, s43
	s_nop 0
	global_load_lds_dwordx4 v148, s[100:101]
	s_add_u32 s86, s86, 0x80
	s_addc_u32 s87, s87, 0
	s_add_i32 m0, s43, 0x2000
	s_nop 0
	global_load_lds_dwordx4 v152, s[100:101]
	s_mov_b32 m0, s57
	s_nop 0
	global_load_lds_dwordx4 v146, s[86:87]
	s_mov_b32 m0, s58
	s_nop 0
	global_load_lds_dwordx4 v150, s[86:87]
	s_waitcnt vmcnt(8)
	s_waitcnt lgkmcnt(0)
	s_barrier
	s_setprio 1
	v_mfma_f32_16x16x32_bf16 v[60:63], v[130:133], v[200:203], v[60:63]
	v_mfma_f32_16x16x32_bf16 v[56:59], v[138:141], v[200:203], v[56:59]
	v_mfma_f32_16x16x32_bf16 v[44:47], v[130:133], v[208:211], v[44:47]
	v_mfma_f32_16x16x32_bf16 v[40:43], v[138:141], v[208:211], v[40:43]
	v_mfma_f32_16x16x32_bf16 v[28:31], v[130:133], v[222:225], v[28:31]
	v_mfma_f32_16x16x32_bf16 v[24:27], v[138:141], v[222:225], v[24:27]
	v_mfma_f32_16x16x32_bf16 v[12:15], v[130:133], v[230:233], v[12:15]
	v_mfma_f32_16x16x32_bf16 v[8:11], v[138:141], v[230:233], v[8:11]
	v_mfma_f32_16x16x32_bf16 v[60:63], v[134:137], v[204:207], v[60:63]
	v_mfma_f32_16x16x32_bf16 v[56:59], v[180:183], v[204:207], v[56:59]
	v_mfma_f32_16x16x32_bf16 v[44:47], v[134:137], v[218:221], v[44:47]
	v_mfma_f32_16x16x32_bf16 v[40:43], v[180:183], v[218:221], v[40:43]
	v_mfma_f32_16x16x32_bf16 v[28:31], v[134:137], v[226:229], v[28:31]
	v_mfma_f32_16x16x32_bf16 v[24:27], v[180:183], v[226:229], v[24:27]
	v_mfma_f32_16x16x32_bf16 v[12:15], v[134:137], v[234:237], v[12:15]
	v_mfma_f32_16x16x32_bf16 v[8:11], v[180:183], v[234:237], v[8:11]
	s_setprio 0
	s_setprio 1
	v_mfma_f32_16x16x32_bf16 v[52:55], v[184:187], v[200:203], v[52:55]
	v_mfma_f32_16x16x32_bf16 v[48:51], v[192:195], v[200:203], v[48:51]
	v_mfma_f32_16x16x32_bf16 v[36:39], v[184:187], v[208:211], v[36:39]
	v_mfma_f32_16x16x32_bf16 v[32:35], v[192:195], v[208:211], v[32:35]
	v_mfma_f32_16x16x32_bf16 v[20:23], v[184:187], v[222:225], v[20:23]
	v_mfma_f32_16x16x32_bf16 v[16:19], v[192:195], v[222:225], v[16:19]
	v_mfma_f32_16x16x32_bf16 v[4:7], v[184:187], v[230:233], v[4:7]
	v_mfma_f32_16x16x32_bf16 v[0:3], v[192:195], v[230:233], v[0:3]
	v_mfma_f32_16x16x32_bf16 v[52:55], v[188:191], v[204:207], v[52:55]
	v_mfma_f32_16x16x32_bf16 v[48:51], v[196:199], v[204:207], v[48:51]
	v_mfma_f32_16x16x32_bf16 v[36:39], v[188:191], v[218:221], v[36:39]
	v_mfma_f32_16x16x32_bf16 v[32:35], v[196:199], v[218:221], v[32:35]
	v_mfma_f32_16x16x32_bf16 v[20:23], v[188:191], v[226:229], v[20:23]
	v_mfma_f32_16x16x32_bf16 v[16:19], v[196:199], v[226:229], v[16:19]
	v_mfma_f32_16x16x32_bf16 v[4:7], v[188:191], v[234:237], v[4:7]
	v_mfma_f32_16x16x32_bf16 v[0:3], v[196:199], v[234:237], v[0:3]
	s_setprio 0
	s_barrier
	s_add_u32 s82, s82, 0x100
	s_addc_u32 s83, s83, 0
	s_add_u32 s81, s81, 0x100
	s_addc_u32 s91, s91, 0
	s_cmp_ge_u32 s98, s60
	s_cbranch_scc1 .LBB0_107
	s_branch .LBB0_105
; #define PG8_STAGE(bufoff, gbase, voff) do { _Pragma("unroll") for (int _i = 0; _i < 2; ++_i) \
;         __builtin_amdgcn_global_load_lds((const unsigned*)((const char*)(gbase) + (voff)[_i]), (LAS unsigned*)(lds + (bufoff) + ldsw + _i * 8192), 16, 0, 0); } while (0)
; #define PG8_LDA(dst, b, h) do { _Pragma("unroll") for (int m = 0; m < 4; ++m) _Pragma("unroll") for (int k = 0; k < 2; ++k) dst[m][k] = *(const LAS bf16x8*)(lds + PG8_SA(b, h) + aoff + m * 2048 + k * 1024); } while (0)
; #define PG8_LDB(dst, b, h) do { _Pragma("unroll") for (int n = 0; n < 2; ++n) _Pragma("unroll") for (int k = 0; k < 2; ++k) dst[n][k] = *(const LAS bf16x8*)(lds + PG8_SB(b, h) + boff + n * 2048 + k * 1024); } while (0)
; #define PG8_MMA(ai, bj, At, Bt) do { __builtin_amdgcn_s_setprio(1); _Pragma("unroll") for (int m = 0; m < 4; ++m) _Pragma("unroll") for (int n = 0; n < 2; ++n) _Pragma("unroll") for (int k = 0; k < 2; ++k) \
;         acc[ai][bj][m][n] = __builtin_amdgcn_mfma_f32_16x16x32_bf16(Bt[n][k], At[m][k], acc[ai][bj][m][n], 0, 0, 0); __builtin_amdgcn_s_setprio(0); } while (0)
; #define PG8_BAR __builtin_amdgcn_s_barrier()
; __device__ __forceinline__ void gemm_phase(LAS unsigned char* lds, const GP p, const int tid) {
;     ...
;         for (int t = 0; t < nt; t += 2) {
;             const bool last = (t == nt - 2);
;             if (last && p.mode != 1) {
;                 const float* rp = p.rs + cur.pm * BM + wr * 64 + fr;
; #pragma unroll
;                 for (int ai = 0; ai < 2; ++ai)
; #pragma unroll
;                     for (int m = 0; m < 4; ++m) rsv[ai][m] = rp[ai * HALF + m * 16];
;             }
;             const char* a1 = cA + (size_t)(t + 1) * kstep;
;             const char* a2 = last ? nA : cA + (size_t)(t + 2) * kstep; const char* b2 = last ? nB : cB + (size_t)(t + 2) * kstep;
;             const char* a3 = a2 + kstep; const char* b3 = b2 + kstep;
;             PG8_LDB(B0, 0, 0); PG8_LDB(B1, 0, 1); PG8_SCHED; PG8_LDA(At, 0, 0); PG8_STAGE(PG8_SA(1, 1), a1 + hstep, voffA);
;             PG8_WAIT_V(8); PG8_WAIT_L(0); PG8_BAR; PG8_MMA(0, 0, At, B0); PG8_MMA(0, 1, At, B1); PG8_BAR; PG8_SCHED;
;             PG8_LDA(At, 0, 1); PG8_STAGE(PG8_SB(0, 0), b2, voffB); PG8_STAGE(PG8_SB(0, 1), b2 + hstep, voffB); PG8_STAGE(PG8_SA(0, 0), a2, voffA);
;             PG8_WAIT_V(8); PG8_WAIT_L(0); PG8_BAR; PG8_MMA(1, 0, At, B0); PG8_MMA(1, 1, At, B1); PG8_BAR; PG8_SCHED;
.LBB0_104:
	ds_read_b128 v[130:133], v238
	ds_read_b128 v[134:137], v238 offset:1024
	ds_read_b128 v[138:141], v238 offset:2048
	ds_read_b128 v[180:183], v238 offset:3072
	ds_read_b128 v[184:187], v239
	ds_read_b128 v[188:191], v239 offset:1024
	ds_read_b128 v[192:195], v239 offset:2048
	ds_read_b128 v[196:199], v239 offset:3072
	ds_read_b128 v[200:203], v167
	ds_read_b128 v[204:207], v167 offset:1024
	ds_read_b128 v[208:211], v167 offset:2048
	ds_read_b128 v[218:221], v167 offset:3072
	ds_read_b128 v[222:225], v167 offset:4096
	ds_read_b128 v[226:229], v167 offset:5120
	ds_read_b128 v[230:233], v167 offset:6144
	ds_read_b128 v[234:237], v167 offset:7168
	s_add_i32 s98, s98, 2
	s_add_u32 s43, s82, 0x80
	s_addc_u32 s99, s83, 0
	s_and_b64 s[86:87], s[84:85], exec
	s_cselect_b32 s87, s77, s99
	s_cselect_b32 s86, s76, s43
	s_add_i32 s43, 0, 0x10000
	s_and_b64 s[84:85], s[84:85], exec
	s_cselect_b32 s85, s79, s91
	s_cselect_b32 s84, s78, s81
	s_add_i32 m0, s53, 0xc000
	s_add_i32 s99, 0, 0x14000
	global_load_lds_dwordx4 v160, s[82:83]
	s_add_i32 m0, s53, 0xe000
	s_nop 0
	global_load_lds_dwordx4 v162, s[82:83]
	s_waitcnt vmcnt(8)
	s_waitcnt lgkmcnt(0)
	s_barrier
	s_setprio 1
	v_mfma_f32_16x16x32_bf16 v[124:127], v[130:133], v[200:203], v[124:127]
	v_mfma_f32_16x16x32_bf16 v[120:123], v[138:141], v[200:203], v[120:123]
	v_mfma_f32_16x16x32_bf16 v[108:111], v[130:133], v[208:211], v[108:111]
	v_mfma_f32_16x16x32_bf16 v[104:107], v[138:141], v[208:211], v[104:107]
	v_mfma_f32_16x16x32_bf16 v[92:95], v[130:133], v[222:225], v[92:95]
	v_mfma_f32_16x16x32_bf16 v[88:91], v[138:141], v[222:225], v[88:91]
	v_mfma_f32_16x16x32_bf16 v[76:79], v[130:133], v[230:233], v[76:79]
	v_mfma_f32_16x16x32_bf16 v[72:75], v[138:141], v[230:233], v[72:75]
	v_mfma_f32_16x16x32_bf16 v[124:127], v[134:137], v[204:207], v[124:127]
	v_mfma_f32_16x16x32_bf16 v[120:123], v[180:183], v[204:207], v[120:123]
	v_mfma_f32_16x16x32_bf16 v[108:111], v[134:137], v[218:221], v[108:111]
	v_mfma_f32_16x16x32_bf16 v[104:107], v[180:183], v[218:221], v[104:107]
	v_mfma_f32_16x16x32_bf16 v[92:95], v[134:137], v[226:229], v[92:95]
	v_mfma_f32_16x16x32_bf16 v[88:91], v[180:183], v[226:229], v[88:91]
	v_mfma_f32_16x16x32_bf16 v[76:79], v[134:137], v[234:237], v[76:79]
	v_mfma_f32_16x16x32_bf16 v[72:75], v[180:183], v[234:237], v[72:75]
	s_setprio 0
	s_setprio 1
	v_mfma_f32_16x16x32_bf16 v[116:119], v[184:187], v[200:203], v[116:119]
	v_mfma_f32_16x16x32_bf16 v[112:115], v[192:195], v[200:203], v[112:115]
	v_mfma_f32_16x16x32_bf16 v[100:103], v[184:187], v[208:211], v[100:103]
	v_mfma_f32_16x16x32_bf16 v[96:99], v[192:195], v[208:211], v[96:99]
	v_mfma_f32_16x16x32_bf16 v[84:87], v[184:187], v[222:225], v[84:87]
	v_mfma_f32_16x16x32_bf16 v[80:83], v[192:195], v[222:225], v[80:83]
	v_mfma_f32_16x16x32_bf16 v[68:71], v[184:187], v[230:233], v[68:71]
	v_mfma_f32_16x16x32_bf16 v[64:67], v[192:195], v[230:233], v[64:67]
	v_mfma_f32_16x16x32_bf16 v[116:119], v[188:191], v[204:207], v[116:119]
	v_mfma_f32_16x16x32_bf16 v[112:115], v[196:199], v[204:207], v[112:115]
	v_mfma_f32_16x16x32_bf16 v[100:103], v[188:191], v[218:221], v[100:103]
	v_mfma_f32_16x16x32_bf16 v[96:99], v[196:199], v[218:221], v[96:99]
	v_mfma_f32_16x16x32_bf16 v[84:87], v[188:191], v[226:229], v[84:87]
	v_mfma_f32_16x16x32_bf16 v[80:83], v[196:199], v[226:229], v[80:83]
	v_mfma_f32_16x16x32_bf16 v[68:71], v[188:191], v[234:237], v[68:71]
	v_mfma_f32_16x16x32_bf16 v[64:67], v[196:199], v[234:237], v[64:67]
	s_setprio 0
	s_barrier
	s_add_i32 s43, s43, s52
	s_mov_b64 s[100:101], s[84:85]
	s_mov_b32 m0, s43
	ds_read_b128 v[200:203], v167 offset:16384
	ds_read_b128 v[204:207], v167 offset:17408
	ds_read_b128 v[208:211], v167 offset:18432
	ds_read_b128 v[218:221], v167 offset:19456
	ds_read_b128 v[222:225], v167 offset:20480
	ds_read_b128 v[226:229], v167 offset:21504
	ds_read_b128 v[230:233], v167 offset:22528
	ds_read_b128 v[234:237], v167 offset:23552
	global_load_lds_dwordx4 v148, s[84:85]
	s_add_i32 m0, s43, 0x2000
	s_add_i32 s43, s99, s52
	global_load_lds_dwordx4 v152, s[84:85]
	s_add_u32 s84, s84, s74
	s_addc_u32 s85, s85, 0
	s_mov_b32 m0, s43
	s_nop 0
	global_load_lds_dwordx4 v148, s[84:85]
	s_add_i32 m0, s43, 0x2000
	s_nop 0
	global_load_lds_dwordx4 v152, s[84:85]
	s_mov_b32 m0, s53
	s_nop 0
	global_load_lds_dwordx4 v146, s[86:87]
	s_mov_b32 m0, s54
	s_nop 0
	global_load_lds_dwordx4 v150, s[86:87]
	s_waitcnt vmcnt(8)
	s_waitcnt lgkmcnt(0)
	s_barrier
	s_setprio 1
	v_mfma_f32_16x16x32_bf16 v[60:63], v[130:133], v[200:203], v[60:63]
	v_mfma_f32_16x16x32_bf16 v[56:59], v[138:141], v[200:203], v[56:59]
	v_mfma_f32_16x16x32_bf16 v[44:47], v[130:133], v[208:211], v[44:47]
	v_mfma_f32_16x16x32_bf16 v[40:43], v[138:141], v[208:211], v[40:43]
	v_mfma_f32_16x16x32_bf16 v[28:31], v[130:133], v[222:225], v[28:31]
	v_mfma_f32_16x16x32_bf16 v[24:27], v[138:141], v[222:225], v[24:27]
	v_mfma_f32_16x16x32_bf16 v[12:15], v[130:133], v[230:233], v[12:15]
	v_mfma_f32_16x16x32_bf16 v[8:11], v[138:141], v[230:233], v[8:11]
	v_mfma_f32_16x16x32_bf16 v[60:63], v[134:137], v[204:207], v[60:63]
	v_mfma_f32_16x16x32_bf16 v[56:59], v[180:183], v[204:207], v[56:59]
	v_mfma_f32_16x16x32_bf16 v[44:47], v[134:137], v[218:221], v[44:47]
	v_mfma_f32_16x16x32_bf16 v[40:43], v[180:183], v[218:221], v[40:43]
	v_mfma_f32_16x16x32_bf16 v[28:31], v[134:137], v[226:229], v[28:31]
	v_mfma_f32_16x16x32_bf16 v[24:27], v[180:183], v[226:229], v[24:27]
	v_mfma_f32_16x16x32_bf16 v[12:15], v[134:137], v[234:237], v[12:15]
	v_mfma_f32_16x16x32_bf16 v[8:11], v[180:183], v[234:237], v[8:11]
	s_setprio 0
	s_setprio 1
	v_mfma_f32_16x16x32_bf16 v[52:55], v[184:187], v[200:203], v[52:55]
	v_mfma_f32_16x16x32_bf16 v[48:51], v[192:195], v[200:203], v[48:51]
	v_mfma_f32_16x16x32_bf16 v[36:39], v[184:187], v[208:211], v[36:39]
	v_mfma_f32_16x16x32_bf16 v[32:35], v[192:195], v[208:211], v[32:35]
	v_mfma_f32_16x16x32_bf16 v[20:23], v[184:187], v[222:225], v[20:23]
	v_mfma_f32_16x16x32_bf16 v[16:19], v[192:195], v[222:225], v[16:19]
	v_mfma_f32_16x16x32_bf16 v[4:7], v[184:187], v[230:233], v[4:7]
	v_mfma_f32_16x16x32_bf16 v[0:3], v[192:195], v[230:233], v[0:3]
	v_mfma_f32_16x16x32_bf16 v[52:55], v[188:191], v[204:207], v[52:55]
	v_mfma_f32_16x16x32_bf16 v[48:51], v[196:199], v[204:207], v[48:51]
	v_mfma_f32_16x16x32_bf16 v[36:39], v[188:191], v[218:221], v[36:39]
	v_mfma_f32_16x16x32_bf16 v[32:35], v[196:199], v[218:221], v[32:35]
	v_mfma_f32_16x16x32_bf16 v[20:23], v[188:191], v[226:229], v[20:23]
	v_mfma_f32_16x16x32_bf16 v[16:19], v[196:199], v[226:229], v[16:19]
	v_mfma_f32_16x16x32_bf16 v[4:7], v[188:191], v[234:237], v[4:7]
	v_mfma_f32_16x16x32_bf16 v[0:3], v[196:199], v[234:237], v[0:3]
	s_setprio 0
	s_barrier
; #define PG8_STAGE(bufoff, gbase, voff) do { _Pragma("unroll") for (int _i = 0; _i < 2; ++_i) \
;         __builtin_amdgcn_global_load_lds((const unsigned*)((const char*)(gbase) + (voff)[_i]), (LAS unsigned*)(lds + (bufoff) + ldsw + _i * 8192), 16, 0, 0); } while (0)
; #define PG8_LDA(dst, b, h) do { _Pragma("unroll") for (int m = 0; m < 4; ++m) _Pragma("unroll") for (int k = 0; k < 2; ++k) dst[m][k] = *(const LAS bf16x8*)(lds + PG8_SA(b, h) + aoff + m * 2048 + k * 1024); } while (0)
; #define PG8_LDB(dst, b, h) do { _Pragma("unroll") for (int n = 0; n < 2; ++n) _Pragma("unroll") for (int k = 0; k < 2; ++k) dst[n][k] = *(const LAS bf16x8*)(lds + PG8_SB(b, h) + boff + n * 2048 + k * 1024); } while (0)
; #define PG8_MMA(ai, bj, At, Bt) do { __builtin_amdgcn_s_setprio(1); _Pragma("unroll") for (int m = 0; m < 4; ++m) _Pragma("unroll") for (int n = 0; n < 2; ++n) _Pragma("unroll") for (int k = 0; k < 2; ++k) \
;         acc[ai][bj][m][n] = __builtin_amdgcn_mfma_f32_16x16x32_bf16(Bt[n][k], At[m][k], acc[ai][bj][m][n], 0, 0, 0); __builtin_amdgcn_s_setprio(0); } while (0)
; #define PG8_WAIT_V(n) asm volatile("s_waitcnt vmcnt(" #n ")" ::: "memory")
; #define PG8_WAIT_L(n) asm volatile("s_waitcnt lgkmcnt(" #n ")" ::: "memory")
; #define PG8_BAR __builtin_amdgcn_s_barrier()
; #define PG8_SCHED __builtin_amdgcn_sched_barrier(0)
; __device__ __forceinline__ void gemm_phase(LAS unsigned char* lds, const GP p, const int tid) {
;     ...
;             PG8_LDB(B0, 1, 0); PG8_LDB(B1, 1, 1); PG8_SCHED; PG8_LDA(At, 1, 0); PG8_STAGE(PG8_SA(0, 1), a2 + hstep, voffA);
;             PG8_WAIT_V(8); PG8_WAIT_L(0); PG8_BAR; PG8_MMA(0, 0, At, B0); PG8_MMA(0, 1, At, B1); PG8_BAR; PG8_SCHED;
;             PG8_LDA(At, 1, 1); PG8_STAGE(PG8_SB(1, 0), b3, voffB); PG8_STAGE(PG8_SB(1, 1), b3 + hstep, voffB); PG8_STAGE(PG8_SA(1, 0), a3, voffA);
;             PG8_WAIT_V(8); PG8_WAIT_L(0); PG8_BAR; PG8_MMA(1, 0, At, B0); PG8_MMA(1, 1, At, B1); PG8_BAR; PG8_SCHED;
;         }
	s_add_i32 s43, 0, 0x18000
	s_add_i32 s99, 0, 0x1c000
	ds_read_b128 v[130:133], v240
	ds_read_b128 v[134:137], v240 offset:1024
	ds_read_b128 v[138:141], v240 offset:2048
	ds_read_b128 v[180:183], v240 offset:3072
	ds_read_b128 v[184:187], v241
	ds_read_b128 v[188:191], v241 offset:1024
	ds_read_b128 v[192:195], v241 offset:2048
	ds_read_b128 v[196:199], v241 offset:3072
	s_add_u32 s84, s86, s74
	s_addc_u32 s85, s87, 0
	s_mov_b32 m0, s55
	ds_read_b128 v[200:203], v167 offset:32768
	ds_read_b128 v[204:207], v167 offset:33792
	ds_read_b128 v[208:211], v167 offset:34816
	ds_read_b128 v[218:221], v167 offset:35840
	ds_read_b128 v[222:225], v167 offset:36864
	ds_read_b128 v[226:229], v167 offset:37888
	ds_read_b128 v[230:233], v167 offset:38912
	ds_read_b128 v[234:237], v167 offset:39936
	global_load_lds_dwordx4 v146, s[84:85]
	s_mov_b32 m0, s56
	s_nop 0
	global_load_lds_dwordx4 v150, s[84:85]
	s_waitcnt vmcnt(8)
	s_waitcnt lgkmcnt(0)
	s_barrier
	s_setprio 1
	v_mfma_f32_16x16x32_bf16 v[124:127], v[130:133], v[200:203], v[124:127]
	v_mfma_f32_16x16x32_bf16 v[120:123], v[138:141], v[200:203], v[120:123]
	v_mfma_f32_16x16x32_bf16 v[108:111], v[130:133], v[208:211], v[108:111]
	v_mfma_f32_16x16x32_bf16 v[104:107], v[138:141], v[208:211], v[104:107]
	v_mfma_f32_16x16x32_bf16 v[92:95], v[130:133], v[222:225], v[92:95]
	v_mfma_f32_16x16x32_bf16 v[88:91], v[138:141], v[222:225], v[88:91]
	v_mfma_f32_16x16x32_bf16 v[76:79], v[130:133], v[230:233], v[76:79]
	v_mfma_f32_16x16x32_bf16 v[72:75], v[138:141], v[230:233], v[72:75]
	v_mfma_f32_16x16x32_bf16 v[124:127], v[134:137], v[204:207], v[124:127]
	v_mfma_f32_16x16x32_bf16 v[120:123], v[180:183], v[204:207], v[120:123]
	v_mfma_f32_16x16x32_bf16 v[108:111], v[134:137], v[218:221], v[108:111]
	v_mfma_f32_16x16x32_bf16 v[104:107], v[180:183], v[218:221], v[104:107]
	v_mfma_f32_16x16x32_bf16 v[92:95], v[134:137], v[226:229], v[92:95]
	v_mfma_f32_16x16x32_bf16 v[88:91], v[180:183], v[226:229], v[88:91]
	v_mfma_f32_16x16x32_bf16 v[76:79], v[134:137], v[234:237], v[76:79]
	v_mfma_f32_16x16x32_bf16 v[72:75], v[180:183], v[234:237], v[72:75]
	s_setprio 0
	s_setprio 1
	v_mfma_f32_16x16x32_bf16 v[116:119], v[184:187], v[200:203], v[116:119]
	v_mfma_f32_16x16x32_bf16 v[112:115], v[192:195], v[200:203], v[112:115]
	v_mfma_f32_16x16x32_bf16 v[100:103], v[184:187], v[208:211], v[100:103]
	v_mfma_f32_16x16x32_bf16 v[96:99], v[192:195], v[208:211], v[96:99]
	v_mfma_f32_16x16x32_bf16 v[84:87], v[184:187], v[222:225], v[84:87]
	v_mfma_f32_16x16x32_bf16 v[80:83], v[192:195], v[222:225], v[80:83]
	v_mfma_f32_16x16x32_bf16 v[68:71], v[184:187], v[230:233], v[68:71]
	v_mfma_f32_16x16x32_bf16 v[64:67], v[192:195], v[230:233], v[64:67]
	v_mfma_f32_16x16x32_bf16 v[116:119], v[188:191], v[204:207], v[116:119]
	v_mfma_f32_16x16x32_bf16 v[112:115], v[196:199], v[204:207], v[112:115]
	v_mfma_f32_16x16x32_bf16 v[100:103], v[188:191], v[218:221], v[100:103]
	v_mfma_f32_16x16x32_bf16 v[96:99], v[196:199], v[218:221], v[96:99]
	v_mfma_f32_16x16x32_bf16 v[84:87], v[188:191], v[226:229], v[84:87]
	v_mfma_f32_16x16x32_bf16 v[80:83], v[196:199], v[226:229], v[80:83]
	v_mfma_f32_16x16x32_bf16 v[68:71], v[188:191], v[234:237], v[68:71]
	v_mfma_f32_16x16x32_bf16 v[64:67], v[196:199], v[234:237], v[64:67]
	s_setprio 0
	s_barrier
	s_add_i32 s43, s43, s52
	s_add_u32 s100, s100, 0x80
	s_addc_u32 s101, s101, 0
	s_mov_b32 m0, s43
	ds_read_b128 v[200:203], v167 offset:49152
	ds_read_b128 v[204:207], v167 offset:50176
	ds_read_b128 v[208:211], v167 offset:51200
	ds_read_b128 v[218:221], v167 offset:52224
	ds_read_b128 v[222:225], v167 offset:53248
	ds_read_b128 v[226:229], v167 offset:54272
	ds_read_b128 v[230:233], v167 offset:55296
	ds_read_b128 v[234:237], v167 offset:56320
	global_load_lds_dwordx4 v148, s[100:101]
	s_add_i32 m0, s43, 0x2000
	s_add_i32 s43, s99, s52
	global_load_lds_dwordx4 v152, s[100:101]
	s_add_u32 s100, s100, s74
	s_addc_u32 s101, s101, 0
	s_mov_b32 m0, s43
	s_nop 0
	global_load_lds_dwordx4 v148, s[100:101]
	s_add_u32 s86, s86, 0x80
	s_addc_u32 s87, s87, 0
	s_add_i32 m0, s43, 0x2000
	s_nop 0
	global_load_lds_dwordx4 v152, s[100:101]
	s_mov_b32 m0, s57
	s_nop 0
	global_load_lds_dwordx4 v146, s[86:87]
	s_mov_b32 m0, s58
	s_nop 0
	global_load_lds_dwordx4 v150, s[86:87]
	s_waitcnt vmcnt(8)
	s_waitcnt lgkmcnt(0)
	s_barrier
	s_setprio 1
	v_mfma_f32_16x16x32_bf16 v[60:63], v[130:133], v[200:203], v[60:63]
	v_mfma_f32_16x16x32_bf16 v[56:59], v[138:141], v[200:203], v[56:59]
	v_mfma_f32_16x16x32_bf16 v[44:47], v[130:133], v[208:211], v[44:47]
	v_mfma_f32_16x16x32_bf16 v[40:43], v[138:141], v[208:211], v[40:43]
	v_mfma_f32_16x16x32_bf16 v[28:31], v[130:133], v[222:225], v[28:31]
	v_mfma_f32_16x16x32_bf16 v[24:27], v[138:141], v[222:225], v[24:27]
	v_mfma_f32_16x16x32_bf16 v[12:15], v[130:133], v[230:233], v[12:15]
	v_mfma_f32_16x16x32_bf16 v[8:11], v[138:141], v[230:233], v[8:11]
	v_mfma_f32_16x16x32_bf16 v[60:63], v[134:137], v[204:207], v[60:63]
	v_mfma_f32_16x16x32_bf16 v[56:59], v[180:183], v[204:207], v[56:59]
	v_mfma_f32_16x16x32_bf16 v[44:47], v[134:137], v[218:221], v[44:47]
	v_mfma_f32_16x16x32_bf16 v[40:43], v[180:183], v[218:221], v[40:43]
	v_mfma_f32_16x16x32_bf16 v[28:31], v[134:137], v[226:229], v[28:31]
	v_mfma_f32_16x16x32_bf16 v[24:27], v[180:183], v[226:229], v[24:27]
	v_mfma_f32_16x16x32_bf16 v[12:15], v[134:137], v[234:237], v[12:15]
	v_mfma_f32_16x16x32_bf16 v[8:11], v[180:183], v[234:237], v[8:11]
	s_setprio 0
	s_setprio 1
	v_mfma_f32_16x16x32_bf16 v[52:55], v[184:187], v[200:203], v[52:55]
	v_mfma_f32_16x16x32_bf16 v[48:51], v[192:195], v[200:203], v[48:51]
	v_mfma_f32_16x16x32_bf16 v[36:39], v[184:187], v[208:211], v[36:39]
	v_mfma_f32_16x16x32_bf16 v[32:35], v[192:195], v[208:211], v[32:35]
	v_mfma_f32_16x16x32_bf16 v[20:23], v[184:187], v[222:225], v[20:23]
	v_mfma_f32_16x16x32_bf16 v[16:19], v[192:195], v[222:225], v[16:19]
	v_mfma_f32_16x16x32_bf16 v[4:7], v[184:187], v[230:233], v[4:7]
	v_mfma_f32_16x16x32_bf16 v[0:3], v[192:195], v[230:233], v[0:3]
	v_mfma_f32_16x16x32_bf16 v[52:55], v[188:191], v[204:207], v[52:55]
	v_mfma_f32_16x16x32_bf16 v[48:51], v[196:199], v[204:207], v[48:51]
	v_mfma_f32_16x16x32_bf16 v[36:39], v[188:191], v[218:221], v[36:39]
	v_mfma_f32_16x16x32_bf16 v[32:35], v[196:199], v[218:221], v[32:35]
	v_mfma_f32_16x16x32_bf16 v[20:23], v[188:191], v[226:229], v[20:23]
	v_mfma_f32_16x16x32_bf16 v[16:19], v[196:199], v[226:229], v[16:19]
	v_mfma_f32_16x16x32_bf16 v[4:7], v[188:191], v[234:237], v[4:7]
	v_mfma_f32_16x16x32_bf16 v[0:3], v[196:199], v[234:237], v[0:3]
	s_setprio 0
	s_barrier
	s_add_u32 s82, s82, 0x100
	s_addc_u32 s83, s83, 0
	s_add_u32 s81, s81, 0x100
	s_addc_u32 s91, s91, 0
	s_cmp_ge_u32 s98, s60
	s_cbranch_scc1 .LBB0_107
